# SwiGLU GEMM epilogue rewritten: packed f32 mul/add, 8 independent chains interleaved (no s_nop stalls), same f32 math order
# speedup vs baseline: 1.0070x; 1.0070x over previous
; #define PG8_STAGE(bufoff, gbase, voff) do { _Pragma("unroll") for (int _i = 0; _i < 2; ++_i) \
;         __builtin_amdgcn_global_load_lds((const unsigned*)((const char*)(gbase) + (voff)[_i]), (LAS unsigned*)(lds + (bufoff) + ldsw + _i * 8192), 16, 0, 0); } while (0)
; #define PG8_LDA(dst, b, h) do { _Pragma("unroll") for (int m = 0; m < 4; ++m) _Pragma("unroll") for (int k = 0; k < 2; ++k) dst[m][k] = *(const LAS bf16x8*)(lds + PG8_SA(b, h) + aoff + m * 2048 + k * 1024); } while (0)
; #define PG8_LDB(dst, b, h) do { _Pragma("unroll") for (int n = 0; n < 2; ++n) _Pragma("unroll") for (int k = 0; k < 2; ++k) dst[n][k] = *(const LAS bf16x8*)(lds + PG8_SB(b, h) + boff + n * 2048 + k * 1024); } while (0)
; #define PG8_MMA(ai, bj, At, Bt) do { __builtin_amdgcn_s_setprio(1); _Pragma("unroll") for (int m = 0; m < 4; ++m) _Pragma("unroll") for (int n = 0; n < 2; ++n) _Pragma("unroll") for (int k = 0; k < 2; ++k) \
;         acc[ai][bj][m][n] = __builtin_amdgcn_mfma_f32_16x16x32_bf16(Bt[n][k], At[m][k], acc[ai][bj][m][n], 0, 0, 0); __builtin_amdgcn_s_setprio(0); } while (0)
; #define PG8_WAIT_V(n) asm volatile("s_waitcnt vmcnt(" #n ")" ::: "memory")
; #define PG8_WAIT_L(n) asm volatile("s_waitcnt lgkmcnt(" #n ")" ::: "memory")
; #define PG8_BAR __builtin_amdgcn_s_barrier()
; #define PG8_SCHED __builtin_amdgcn_sched_barrier(0)
; template <class Epi, class Sched>
; __device__ __forceinline__ void gemm_phase(LAS unsigned char* lds, const Gemm g, const Sched& S, const Epi& E, const Ids I) {
;     ...
;             PG8_LDB(B0, 0, 0); PG8_SCHED; PG8_LDA(At, 0, 0); PG8_STAGE(PG8_SA(1, 1), a1 + hstep, voffA);
;             PG8_WAIT_L(8); PG8_BAR; PG8_WAIT_L(0); PG8_MMA(0, 0, At, B0); PG8_BAR; PG8_SCHED;
;             PG8_LDB(B1, 0, 1); PG8_STAGE(PG8_SB(0, 0), b2, voffB);
;             PG8_BAR; PG8_WAIT_L(0); PG8_MMA(0, 1, At, B1); PG8_BAR;
;             PG8_LDA(At, 0, 1); PG8_STAGE(PG8_SA(0, 0), a2, voffA);
;             PG8_BAR; PG8_WAIT_L(0); PG8_MMA(1, 0, At, B0); PG8_BAR; PG8_SCHED;
;             PG8_STAGE(PG8_SB(0, 1), b2 + hstep, voffB);
;             PG8_WAIT_V(6); PG8_BAR; PG8_MMA(1, 1, At, B1); PG8_BAR;
;             PG8_LDB(B0, 1, 0); PG8_SCHED; PG8_LDA(At, 1, 0); PG8_STAGE(PG8_SA(0, 1), a2 + hstep, voffA);
;             PG8_WAIT_L(8); PG8_BAR; PG8_WAIT_L(0); PG8_MMA(0, 0, At, B0); PG8_BAR; PG8_SCHED;
.LBB0_408:
	s_add_u32 s20, s18, 0xfffc0080
	s_addc_u32 s21, s19, -1
	s_add_i32 s39, 0, 0x10000
	v_add_u32_e32 v134, s39, v137
	ds_read_b128 v[140:143], v134
	ds_read_b128 v[152:155], v134 offset:1024
	ds_read_b128 v[156:159], v134 offset:2048
	ds_read_b128 v[160:163], v134 offset:3072
	s_cmp_eq_u32 s38, 12
	s_cselect_b32 s23, s3, s21
	s_cselect_b32 s22, s9, s20
	s_cselect_b32 s21, s7, s37
	s_cselect_b32 s20, s35, s36
	v_lshl_add_u64 v[134:135], s[18:19], 0, v[130:131]
	s_add_i32 m0, s17, 0xc000
	ds_read_b128 v[164:167], v139
	ds_read_b128 v[168:171], v139 offset:1024
	ds_read_b128 v[188:191], v139 offset:2048
	ds_read_b128 v[192:195], v139 offset:3072
	ds_read_b128 v[196:199], v139 offset:4096
	ds_read_b128 v[200:203], v139 offset:5120
	ds_read_b128 v[204:207], v139 offset:6144
	ds_read_b128 v[208:211], v139 offset:7168
	global_load_lds_dwordx4 v[134:135], off
	v_lshl_add_u64 v[134:135], s[18:19], 0, v[132:133]
	s_add_i32 m0, s17, 0xe000
	s_nop 0
	global_load_lds_dwordx4 v[134:135], off
	s_waitcnt lgkmcnt(8)
	s_barrier
	s_waitcnt lgkmcnt(0)
	s_setprio 1
	s_waitcnt lgkmcnt(0)
	v_mfma_f32_16x16x32_bf16 v[124:127], v[140:143], v[164:167], v[124:127]
	v_mfma_f32_16x16x32_bf16 v[116:119], v[156:159], v[164:167], v[116:119]
	v_mfma_f32_16x16x32_bf16 v[108:111], v[140:143], v[188:191], v[108:111]
	v_mfma_f32_16x16x32_bf16 v[100:103], v[156:159], v[188:191], v[100:103]
	v_mfma_f32_16x16x32_bf16 v[92:95], v[140:143], v[196:199], v[92:95]
	v_mfma_f32_16x16x32_bf16 v[84:87], v[156:159], v[196:199], v[84:87]
	v_mfma_f32_16x16x32_bf16 v[76:79], v[140:143], v[204:207], v[76:79]
	v_mfma_f32_16x16x32_bf16 v[68:71], v[156:159], v[204:207], v[68:71]
	v_mfma_f32_16x16x32_bf16 v[124:127], v[152:155], v[168:171], v[124:127]
	v_mfma_f32_16x16x32_bf16 v[116:119], v[160:163], v[168:171], v[116:119]
	v_mfma_f32_16x16x32_bf16 v[108:111], v[152:155], v[192:195], v[108:111]
	v_mfma_f32_16x16x32_bf16 v[100:103], v[160:163], v[192:195], v[100:103]
	v_mfma_f32_16x16x32_bf16 v[92:95], v[152:155], v[200:203], v[92:95]
	v_mfma_f32_16x16x32_bf16 v[84:87], v[160:163], v[200:203], v[84:87]
	v_mfma_f32_16x16x32_bf16 v[76:79], v[152:155], v[208:211], v[76:79]
	v_mfma_f32_16x16x32_bf16 v[68:71], v[160:163], v[208:211], v[68:71]
	s_setprio 0
	s_barrier
	s_add_i32 s42, 0, 0x14000
	v_add_u32_e32 v134, s42, v137
	s_add_i32 s39, s39, s25
	ds_read_b128 v[212:215], v134
	ds_read_b128 v[216:219], v134 offset:1024
	ds_read_b128 v[220:223], v134 offset:2048
	ds_read_b128 v[224:227], v134 offset:3072
	v_lshl_add_u64 v[134:135], s[20:21], 0, v[144:145]
	s_mov_b32 m0, s39
	v_lshl_add_u64 v[172:173], s[20:21], 0, v[128:129]
	global_load_lds_dwordx4 v[134:135], off
	s_add_i32 m0, s39, 0x2000
	s_nop 0
	global_load_lds_dwordx4 v[172:173], off
	s_barrier
	s_waitcnt lgkmcnt(0)
	s_setprio 1
	s_waitcnt lgkmcnt(0)
	v_mfma_f32_16x16x32_bf16 v[120:123], v[212:215], v[164:167], v[120:123]
	v_mfma_f32_16x16x32_bf16 v[112:115], v[220:223], v[164:167], v[112:115]
	v_mfma_f32_16x16x32_bf16 v[104:107], v[212:215], v[188:191], v[104:107]
	v_mfma_f32_16x16x32_bf16 v[96:99], v[220:223], v[188:191], v[96:99]
	v_mfma_f32_16x16x32_bf16 v[88:91], v[212:215], v[196:199], v[88:91]
	v_mfma_f32_16x16x32_bf16 v[80:83], v[220:223], v[196:199], v[80:83]
	v_mfma_f32_16x16x32_bf16 v[72:75], v[212:215], v[204:207], v[72:75]
	v_mfma_f32_16x16x32_bf16 v[64:67], v[220:223], v[204:207], v[64:67]
	v_mfma_f32_16x16x32_bf16 v[120:123], v[216:219], v[168:171], v[120:123]
	v_mfma_f32_16x16x32_bf16 v[112:115], v[224:227], v[168:171], v[112:115]
	v_mfma_f32_16x16x32_bf16 v[104:107], v[216:219], v[192:195], v[104:107]
	v_mfma_f32_16x16x32_bf16 v[96:99], v[224:227], v[192:195], v[96:99]
	v_mfma_f32_16x16x32_bf16 v[88:91], v[216:219], v[200:203], v[88:91]
	v_mfma_f32_16x16x32_bf16 v[80:83], v[224:227], v[200:203], v[80:83]
	v_mfma_f32_16x16x32_bf16 v[72:75], v[216:219], v[208:211], v[72:75]
	v_mfma_f32_16x16x32_bf16 v[64:67], v[224:227], v[208:211], v[64:67]
	s_setprio 0
	s_mov_b32 m0, s17
	v_lshl_add_u64 v[176:177], s[22:23], 0, v[144:145]
	s_barrier
	ds_read_b128 v[164:167], v139 offset:16384
	ds_read_b128 v[168:171], v139 offset:17408
	ds_read_b128 v[188:191], v139 offset:18432
	ds_read_b128 v[192:195], v139 offset:19456
	ds_read_b128 v[196:199], v139 offset:20480
	ds_read_b128 v[200:203], v139 offset:21504
	ds_read_b128 v[204:207], v139 offset:22528
	ds_read_b128 v[208:211], v139 offset:23552
	global_load_lds_dwordx4 v[176:177], off
	v_lshl_add_u64 v[178:179], s[22:23], 0, v[128:129]
	s_mov_b32 m0, s28
	s_nop 0
	global_load_lds_dwordx4 v[178:179], off
	s_barrier
	s_waitcnt lgkmcnt(0)
	s_setprio 1
	s_waitcnt lgkmcnt(0)
	v_mfma_f32_16x16x32_bf16 v[60:63], v[140:143], v[164:167], v[60:63]
	v_mfma_f32_16x16x32_bf16 v[52:55], v[156:159], v[164:167], v[52:55]
	v_mfma_f32_16x16x32_bf16 v[44:47], v[140:143], v[188:191], v[44:47]
	v_mfma_f32_16x16x32_bf16 v[36:39], v[156:159], v[188:191], v[36:39]
	v_mfma_f32_16x16x32_bf16 v[28:31], v[140:143], v[196:199], v[28:31]
	v_mfma_f32_16x16x32_bf16 v[20:23], v[156:159], v[196:199], v[20:23]
	v_mfma_f32_16x16x32_bf16 v[12:15], v[140:143], v[204:207], v[12:15]
	v_mfma_f32_16x16x32_bf16 v[4:7], v[156:159], v[204:207], v[4:7]
	v_mfma_f32_16x16x32_bf16 v[60:63], v[152:155], v[168:171], v[60:63]
	v_mfma_f32_16x16x32_bf16 v[52:55], v[160:163], v[168:171], v[52:55]
	v_mfma_f32_16x16x32_bf16 v[44:47], v[152:155], v[192:195], v[44:47]
	v_mfma_f32_16x16x32_bf16 v[36:39], v[160:163], v[192:195], v[36:39]
	v_mfma_f32_16x16x32_bf16 v[28:31], v[152:155], v[200:203], v[28:31]
	v_mfma_f32_16x16x32_bf16 v[20:23], v[160:163], v[200:203], v[20:23]
	v_mfma_f32_16x16x32_bf16 v[12:15], v[152:155], v[208:211], v[12:15]
	v_mfma_f32_16x16x32_bf16 v[4:7], v[160:163], v[208:211], v[4:7]
	s_setprio 0
	s_barrier
; #define PG8_STAGE(bufoff, gbase, voff) do { _Pragma("unroll") for (int _i = 0; _i < 2; ++_i) \
;         __builtin_amdgcn_global_load_lds((const unsigned*)((const char*)(gbase) + (voff)[_i]), (LAS unsigned*)(lds + (bufoff) + ldsw + _i * 8192), 16, 0, 0); } while (0)
; #define PG8_LDA(dst, b, h) do { _Pragma("unroll") for (int m = 0; m < 4; ++m) _Pragma("unroll") for (int k = 0; k < 2; ++k) dst[m][k] = *(const LAS bf16x8*)(lds + PG8_SA(b, h) + aoff + m * 2048 + k * 1024); } while (0)
; #define PG8_LDB(dst, b, h) do { _Pragma("unroll") for (int n = 0; n < 2; ++n) _Pragma("unroll") for (int k = 0; k < 2; ++k) dst[n][k] = *(const LAS bf16x8*)(lds + PG8_SB(b, h) + boff + n * 2048 + k * 1024); } while (0)
; #define PG8_MMA(ai, bj, At, Bt) do { __builtin_amdgcn_s_setprio(1); _Pragma("unroll") for (int m = 0; m < 4; ++m) _Pragma("unroll") for (int n = 0; n < 2; ++n) _Pragma("unroll") for (int k = 0; k < 2; ++k) \
;         acc[ai][bj][m][n] = __builtin_amdgcn_mfma_f32_16x16x32_bf16(Bt[n][k], At[m][k], acc[ai][bj][m][n], 0, 0, 0); __builtin_amdgcn_s_setprio(0); } while (0)
; #define PG8_WAIT_V(n) asm volatile("s_waitcnt vmcnt(" #n ")" ::: "memory")
; #define PG8_WAIT_L(n) asm volatile("s_waitcnt lgkmcnt(" #n ")" ::: "memory")
; #define PG8_BAR __builtin_amdgcn_s_barrier()
; #define PG8_SCHED __builtin_amdgcn_sched_barrier(0)
; template <class Epi, class Sched>
; __device__ __forceinline__ void gemm_phase(LAS unsigned char* lds, const Gemm g, const Sched& S, const Epi& E, const Ids I) {
;     ...
;             PG8_WAIT_V(6); PG8_BAR; PG8_MMA(1, 1, At, B1); PG8_BAR;
;             PG8_LDB(B0, 1, 0); PG8_SCHED; PG8_LDA(At, 1, 0); PG8_STAGE(PG8_SA(0, 1), a2 + hstep, voffA);
;             PG8_WAIT_L(8); PG8_BAR; PG8_WAIT_L(0); PG8_MMA(0, 0, At, B0); PG8_BAR; PG8_SCHED;
;             PG8_LDB(B1, 1, 1); PG8_STAGE(PG8_SB(1, 0), b3, voffB);
;             PG8_BAR; PG8_WAIT_L(0); PG8_MMA(0, 1, At, B1); PG8_BAR;
;             PG8_LDA(At, 1, 1); PG8_STAGE(PG8_SA(1, 0), a3, voffA);
;             PG8_BAR; PG8_WAIT_L(0); PG8_MMA(1, 0, At, B0); PG8_BAR; PG8_SCHED;
;             PG8_STAGE(PG8_SB(1, 1), b3 + hstep, voffB);
;             PG8_WAIT_V(6); PG8_BAR; PG8_MMA(1, 1, At, B1); PG8_BAR;
	s_add_u32 s40, s20, 0x40000
	s_addc_u32 s41, s21, 0
	s_add_i32 s39, s42, s25
	v_lshl_add_u64 v[140:141], s[40:41], 0, v[144:145]
	s_mov_b32 m0, s39
	s_nop 0
	global_load_lds_dwordx4 v[140:141], off
	v_lshl_add_u64 v[140:141], s[40:41], 0, v[128:129]
	s_add_i32 m0, s39, 0x2000
	s_nop 0
	global_load_lds_dwordx4 v[140:141], off
	s_waitcnt vmcnt(6)
	s_barrier
	s_setprio 1
	v_mfma_f32_16x16x32_bf16 v[56:59], v[212:215], v[164:167], v[56:59]
	v_mfma_f32_16x16x32_bf16 v[48:51], v[220:223], v[164:167], v[48:51]
	v_mfma_f32_16x16x32_bf16 v[40:43], v[212:215], v[188:191], v[40:43]
	v_mfma_f32_16x16x32_bf16 v[32:35], v[220:223], v[188:191], v[32:35]
	v_mfma_f32_16x16x32_bf16 v[24:27], v[212:215], v[196:199], v[24:27]
	v_mfma_f32_16x16x32_bf16 v[16:19], v[220:223], v[196:199], v[16:19]
	v_mfma_f32_16x16x32_bf16 v[8:11], v[212:215], v[204:207], v[8:11]
	v_mfma_f32_16x16x32_bf16 v[0:3], v[220:223], v[204:207], v[0:3]
	v_mfma_f32_16x16x32_bf16 v[56:59], v[216:219], v[168:171], v[56:59]
	v_mfma_f32_16x16x32_bf16 v[48:51], v[224:227], v[168:171], v[48:51]
	v_mfma_f32_16x16x32_bf16 v[40:43], v[216:219], v[192:195], v[40:43]
	v_mfma_f32_16x16x32_bf16 v[32:35], v[224:227], v[192:195], v[32:35]
	v_mfma_f32_16x16x32_bf16 v[24:27], v[216:219], v[200:203], v[24:27]
	v_mfma_f32_16x16x32_bf16 v[16:19], v[224:227], v[200:203], v[16:19]
	v_mfma_f32_16x16x32_bf16 v[8:11], v[216:219], v[208:211], v[8:11]
	v_mfma_f32_16x16x32_bf16 v[0:3], v[224:227], v[208:211], v[0:3]
	s_setprio 0
	s_add_i32 s39, 0, 0x18000
	v_add_u32_e32 v147, s39, v137
	s_barrier
	ds_read_b128 v[140:143], v147
	ds_read_b128 v[152:155], v147 offset:1024
	ds_read_b128 v[156:159], v147 offset:2048
	ds_read_b128 v[160:163], v147 offset:3072
	s_add_u32 s22, s22, 0x40000
	s_addc_u32 s23, s23, 0
	s_mov_b32 m0, s29
	v_lshl_add_u64 v[180:181], s[22:23], 0, v[144:145]
	ds_read_b128 v[164:167], v139 offset:32768
	ds_read_b128 v[168:171], v139 offset:33792
	ds_read_b128 v[188:191], v139 offset:34816
	ds_read_b128 v[192:195], v139 offset:35840
	ds_read_b128 v[196:199], v139 offset:36864
	ds_read_b128 v[200:203], v139 offset:37888
	ds_read_b128 v[204:207], v139 offset:38912
	ds_read_b128 v[208:211], v139 offset:39936
	global_load_lds_dwordx4 v[180:181], off
	v_lshl_add_u64 v[180:181], s[22:23], 0, v[128:129]
	s_mov_b32 m0, s30
	s_nop 0
	global_load_lds_dwordx4 v[180:181], off
	s_waitcnt lgkmcnt(8)
	s_barrier
	s_waitcnt lgkmcnt(0)
	s_setprio 1
	s_waitcnt lgkmcnt(0)
	v_mfma_f32_16x16x32_bf16 v[124:127], v[140:143], v[164:167], v[124:127]
	v_mfma_f32_16x16x32_bf16 v[116:119], v[156:159], v[164:167], v[116:119]
	v_mfma_f32_16x16x32_bf16 v[108:111], v[140:143], v[188:191], v[108:111]
	v_mfma_f32_16x16x32_bf16 v[100:103], v[156:159], v[188:191], v[100:103]
	v_mfma_f32_16x16x32_bf16 v[92:95], v[140:143], v[196:199], v[92:95]
	v_mfma_f32_16x16x32_bf16 v[84:87], v[156:159], v[196:199], v[84:87]
	v_mfma_f32_16x16x32_bf16 v[76:79], v[140:143], v[204:207], v[76:79]
	v_mfma_f32_16x16x32_bf16 v[68:71], v[156:159], v[204:207], v[68:71]
	v_mfma_f32_16x16x32_bf16 v[124:127], v[152:155], v[168:171], v[124:127]
	v_mfma_f32_16x16x32_bf16 v[116:119], v[160:163], v[168:171], v[116:119]
	v_mfma_f32_16x16x32_bf16 v[108:111], v[152:155], v[192:195], v[108:111]
	v_mfma_f32_16x16x32_bf16 v[100:103], v[160:163], v[192:195], v[100:103]
	v_mfma_f32_16x16x32_bf16 v[92:95], v[152:155], v[200:203], v[92:95]
	v_mfma_f32_16x16x32_bf16 v[84:87], v[160:163], v[200:203], v[84:87]
	v_mfma_f32_16x16x32_bf16 v[76:79], v[152:155], v[208:211], v[76:79]
	v_mfma_f32_16x16x32_bf16 v[68:71], v[160:163], v[208:211], v[68:71]
	s_setprio 0
	s_barrier
	s_add_i32 s22, 0, 0x1c000
	s_add_i32 s23, s39, s25
	v_add_u32_e32 v147, s22, v137
	v_lshl_add_u64 v[134:135], v[134:135], 0, s[64:65]
	s_mov_b32 m0, s23
	ds_read_b128 v[212:215], v147
	ds_read_b128 v[216:219], v147 offset:1024
	ds_read_b128 v[220:223], v147 offset:2048
	ds_read_b128 v[224:227], v147 offset:3072
	global_load_lds_dwordx4 v[134:135], off
	v_lshl_add_u64 v[134:135], v[172:173], 0, s[64:65]
	s_add_i32 m0, s23, 0x2000
	s_nop 0
	global_load_lds_dwordx4 v[134:135], off
	s_barrier
	s_waitcnt lgkmcnt(0)
	s_setprio 1
	s_waitcnt lgkmcnt(0)
	v_mfma_f32_16x16x32_bf16 v[120:123], v[212:215], v[164:167], v[120:123]
	v_mfma_f32_16x16x32_bf16 v[112:115], v[220:223], v[164:167], v[112:115]
	v_mfma_f32_16x16x32_bf16 v[104:107], v[212:215], v[188:191], v[104:107]
	v_mfma_f32_16x16x32_bf16 v[96:99], v[220:223], v[188:191], v[96:99]
	v_mfma_f32_16x16x32_bf16 v[88:91], v[212:215], v[196:199], v[88:91]
	v_mfma_f32_16x16x32_bf16 v[80:83], v[220:223], v[196:199], v[80:83]
	v_mfma_f32_16x16x32_bf16 v[72:75], v[212:215], v[204:207], v[72:75]
	v_mfma_f32_16x16x32_bf16 v[64:67], v[220:223], v[204:207], v[64:67]
	v_mfma_f32_16x16x32_bf16 v[120:123], v[216:219], v[168:171], v[120:123]
	v_mfma_f32_16x16x32_bf16 v[112:115], v[224:227], v[168:171], v[112:115]
	v_mfma_f32_16x16x32_bf16 v[104:107], v[216:219], v[192:195], v[104:107]
	v_mfma_f32_16x16x32_bf16 v[96:99], v[224:227], v[192:195], v[96:99]
	v_mfma_f32_16x16x32_bf16 v[88:91], v[216:219], v[200:203], v[88:91]
	v_mfma_f32_16x16x32_bf16 v[80:83], v[224:227], v[200:203], v[80:83]
	v_mfma_f32_16x16x32_bf16 v[72:75], v[216:219], v[208:211], v[72:75]
	v_mfma_f32_16x16x32_bf16 v[64:67], v[224:227], v[208:211], v[64:67]
	s_setprio 0
	s_mov_b32 m0, s31
	v_lshl_add_u64 v[134:135], v[176:177], 0, s[64:65]
	s_barrier
	ds_read_b128 v[164:167], v139 offset:49152
	ds_read_b128 v[168:171], v139 offset:50176
	ds_read_b128 v[188:191], v139 offset:51200
	ds_read_b128 v[192:195], v139 offset:52224
	ds_read_b128 v[196:199], v139 offset:53248
	ds_read_b128 v[200:203], v139 offset:54272
	ds_read_b128 v[204:207], v139 offset:55296
	ds_read_b128 v[208:211], v139 offset:56320
	global_load_lds_dwordx4 v[134:135], off
	v_lshl_add_u64 v[134:135], v[178:179], 0, s[64:65]
	s_mov_b32 m0, s34
	s_nop 0
	global_load_lds_dwordx4 v[134:135], off
	s_barrier
; __device__ __forceinline__ unsigned cvt_pk_bf16(float lo, float hi) { unsigned r; asm("v_cvt_pk_bf16_f32 %0, %1, %2" : "=v"(r) : "v"(lo), "v"(hi)); return r; }
; __device__ __forceinline__ float sigmoidf(float x) { return rcpf(1.0f + __expf(-x)); }
; #define PG8_STAGE(bufoff, gbase, voff) do { _Pragma("unroll") for (int _i = 0; _i < 2; ++_i) \
;         __builtin_amdgcn_global_load_lds((const unsigned*)((const char*)(gbase) + (voff)[_i]), (LAS unsigned*)(lds + (bufoff) + ldsw + _i * 8192), 16, 0, 0); } while (0)
; #define PG8_LDA(dst, b, h) do { _Pragma("unroll") for (int m = 0; m < 4; ++m) _Pragma("unroll") for (int k = 0; k < 2; ++k) dst[m][k] = *(const LAS bf16x8*)(lds + PG8_SA(b, h) + aoff + m * 2048 + k * 1024); } while (0)
; #define PG8_WAIT_V(n) asm volatile("s_waitcnt vmcnt(" #n ")" ::: "memory")
; #define PG8_WAIT_L(n) asm volatile("s_waitcnt lgkmcnt(" #n ")" ::: "memory")
; #define PG8_BAR __builtin_amdgcn_s_barrier()
; #define PG8_SCHED __builtin_amdgcn_sched_barrier(0)
; template <class Epi, class Sched>
; __device__ __forceinline__ void gemm_phase(LAS unsigned char* lds, const Gemm g, const Sched& S, const Epi& E, const Ids I) {
;     ...
;             PG8_BAR; PG8_WAIT_L(0); PG8_MMA(0, 1, At, B1); PG8_BAR;
;             PG8_LDA(At, 1, 1); PG8_STAGE(PG8_SA(1, 0), a3, voffA);
;             PG8_BAR; PG8_WAIT_L(0); PG8_MMA(1, 0, At, B0); PG8_BAR; PG8_SCHED;
;             PG8_STAGE(PG8_SB(1, 1), b3 + hstep, voffB);
;             PG8_WAIT_V(6); PG8_BAR; PG8_MMA(1, 1, At, B1); PG8_BAR;
;     __device__ __forceinline__ void operator()(const f32x4 (&acc)[2][2][4][2], const pg8::Unit& u, int wr, int wc, int fr, int fq) const {
;         const int row0 = u.pm * 256 + wr * 64 + fr, col0 = u.pn * 128 + wc * 32 + 8 * fq;
; #pragma unroll
;         for (int ai = 0; ai < 2; ++ai)
; #pragma unroll
;             for (int m = 0; m < 4; ++m) { bf16_t* rowp = act + (size_t)(row0 + ai * 128 + m * 16) * FF + col0; float o[8];
; #pragma unroll
;                 for (int n = 0; n < 2; ++n) { const f32x4 gv = acc[ai][0][m][n], uv = acc[ai][1][m][n];
; #pragma unroll
;                     for (int j = 0; j < 4; ++j) o[4 * n + j] = gv[j] * sigmoidf(gv[j]) * uv[j]; }
;                 u32x4 w; w.x = cvt_pk_bf16(o[0], o[1]); w.y = cvt_pk_bf16(o[2], o[3]); w.z = cvt_pk_bf16(o[4], o[5]); w.w = cvt_pk_bf16(o[6], o[7]); *(u32x4*)rowp = w; }
	s_waitcnt lgkmcnt(0)
	s_setprio 1
	s_waitcnt lgkmcnt(0)
	v_mfma_f32_16x16x32_bf16 v[60:63], v[140:143], v[164:167], v[60:63]
	v_mfma_f32_16x16x32_bf16 v[52:55], v[156:159], v[164:167], v[52:55]
	v_mfma_f32_16x16x32_bf16 v[44:47], v[140:143], v[188:191], v[44:47]
	v_mfma_f32_16x16x32_bf16 v[36:39], v[156:159], v[188:191], v[36:39]
	v_mfma_f32_16x16x32_bf16 v[28:31], v[140:143], v[196:199], v[28:31]
	v_mfma_f32_16x16x32_bf16 v[20:23], v[156:159], v[196:199], v[20:23]
	v_mfma_f32_16x16x32_bf16 v[12:15], v[140:143], v[204:207], v[12:15]
	v_mfma_f32_16x16x32_bf16 v[4:7], v[156:159], v[204:207], v[4:7]
	v_mfma_f32_16x16x32_bf16 v[60:63], v[152:155], v[168:171], v[60:63]
	v_mfma_f32_16x16x32_bf16 v[52:55], v[160:163], v[168:171], v[52:55]
	v_mfma_f32_16x16x32_bf16 v[44:47], v[152:155], v[192:195], v[44:47]
	v_mfma_f32_16x16x32_bf16 v[36:39], v[160:163], v[192:195], v[36:39]
	v_mfma_f32_16x16x32_bf16 v[28:31], v[152:155], v[200:203], v[28:31]
	v_mfma_f32_16x16x32_bf16 v[20:23], v[160:163], v[200:203], v[20:23]
	v_mfma_f32_16x16x32_bf16 v[12:15], v[152:155], v[208:211], v[12:15]
	v_mfma_f32_16x16x32_bf16 v[4:7], v[160:163], v[208:211], v[4:7]
	s_setprio 0
	s_barrier
	s_add_u32 s20, s20, 0x40080
	s_addc_u32 s21, s21, 0
	s_add_i32 s22, s22, s25
	v_lshl_add_u64 v[134:135], s[20:21], 0, v[144:145]
	s_mov_b32 m0, s22
	s_nop 0
	global_load_lds_dwordx4 v[134:135], off
	v_lshl_add_u64 v[134:135], s[20:21], 0, v[128:129]
	s_add_i32 m0, s22, 0x2000
	s_nop 0
	global_load_lds_dwordx4 v[134:135], off
	s_waitcnt vmcnt(6)
	s_barrier
	s_setprio 1
	v_mfma_f32_16x16x32_bf16 v[56:59], v[212:215], v[164:167], v[56:59]
	v_mfma_f32_16x16x32_bf16 v[48:51], v[220:223], v[164:167], v[48:51]
	v_mfma_f32_16x16x32_bf16 v[40:43], v[212:215], v[188:191], v[40:43]
	v_mfma_f32_16x16x32_bf16 v[32:35], v[220:223], v[188:191], v[32:35]
	v_mfma_f32_16x16x32_bf16 v[24:27], v[212:215], v[196:199], v[24:27]
	v_mfma_f32_16x16x32_bf16 v[16:19], v[220:223], v[196:199], v[16:19]
	v_mfma_f32_16x16x32_bf16 v[8:11], v[212:215], v[204:207], v[8:11]
	v_mfma_f32_16x16x32_bf16 v[0:3], v[220:223], v[204:207], v[0:3]
	v_mfma_f32_16x16x32_bf16 v[56:59], v[216:219], v[168:171], v[56:59]
	v_mfma_f32_16x16x32_bf16 v[48:51], v[224:227], v[168:171], v[48:51]
	v_mfma_f32_16x16x32_bf16 v[40:43], v[216:219], v[192:195], v[40:43]
	v_mfma_f32_16x16x32_bf16 v[32:35], v[224:227], v[192:195], v[32:35]
	v_mfma_f32_16x16x32_bf16 v[24:27], v[216:219], v[200:203], v[24:27]
	v_mfma_f32_16x16x32_bf16 v[16:19], v[224:227], v[200:203], v[16:19]
	v_mfma_f32_16x16x32_bf16 v[8:11], v[216:219], v[208:211], v[8:11]
	v_mfma_f32_16x16x32_bf16 v[0:3], v[224:227], v[208:211], v[0:3]
	s_setprio 0
	s_add_i32 s38, s38, 2
	s_add_u32 s18, s18, 0x100
	s_addc_u32 s19, s19, 0
	s_add_u32 s36, s36, 0x100
	s_addc_u32 s37, s37, 0
	s_cmp_gt_u32 s38, 13
	s_barrier
	s_cbranch_scc0 .LBB0_408
	v_lshl_or_b32 v142, s1, 7, v138
	v_lshl_add_u32 v140, s16, 8, v136
	v_mov_b32_e32 v160, 0xbfb8aa3b
	v_mov_b32_e32 v161, 0xbfb8aa3b
	v_mov_b32_e32 v162, 1.0
	v_mov_b32_e32 v163, 1.0
	v_ashrrev_i32_e32 v143, 31, v142
	v_mov_b64_e32 v[134:135], s[60:61]
	v_lshlrev_b64 v[164:165], 1, v[142:143]
	s_mov_b32 s1, s6
	s_mov_b32 s16, s8
	s_mov_b64 s[20:21], s[14:15]
	v_pk_mul_f32 v[152:153], v[124:125], v[160:161]
	v_pk_mul_f32 v[154:155], v[126:127], v[160:161]
	v_pk_mul_f32 v[156:157], v[116:117], v[160:161]
	v_pk_mul_f32 v[158:159], v[118:119], v[160:161]
	v_exp_f32_e32 v152, v152
	v_exp_f32_e32 v153, v153
	v_exp_f32_e32 v154, v154
	v_exp_f32_e32 v155, v155
	v_exp_f32_e32 v156, v156
	v_exp_f32_e32 v157, v157
	v_exp_f32_e32 v158, v158
	v_exp_f32_e32 v159, v159
	v_mad_i64_i32 v[166:167], s[18:19], v140, s73, v[134:135]
	v_pk_add_f32 v[152:153], v[152:153], v[162:163]
	v_pk_add_f32 v[154:155], v[154:155], v[162:163]
	v_pk_add_f32 v[156:157], v[156:157], v[162:163]
	v_pk_add_f32 v[158:159], v[158:159], v[162:163]
	v_rcp_f32_e32 v152, v152
	v_rcp_f32_e32 v153, v153
	v_rcp_f32_e32 v154, v154
	v_rcp_f32_e32 v155, v155
	v_rcp_f32_e32 v156, v156
	v_rcp_f32_e32 v157, v157
	v_rcp_f32_e32 v158, v158
	v_rcp_f32_e32 v159, v159
	v_lshl_add_u64 v[168:169], v[166:167], 0, v[164:165]
	v_pk_mul_f32 v[124:125], v[124:125], v[152:153]
	v_pk_mul_f32 v[126:127], v[126:127], v[154:155]
	v_pk_mul_f32 v[116:117], v[116:117], v[156:157]
	v_pk_mul_f32 v[118:119], v[118:119], v[158:159]
	v_pk_mul_f32 v[124:125], v[124:125], v[120:121]
	v_pk_mul_f32 v[126:127], v[126:127], v[122:123]
	v_pk_mul_f32 v[116:117], v[116:117], v[112:113]
	v_pk_mul_f32 v[118:119], v[118:119], v[114:115]
	v_cvt_pk_bf16_f32 v120, v124, v125
	v_cvt_pk_bf16_f32 v121, v126, v127
	v_cvt_pk_bf16_f32 v122, v116, v117
	v_cvt_pk_bf16_f32 v123, v118, v119
	global_store_dwordx4 v[168:169], v[120:123], off
	v_pk_mul_f32 v[152:153], v[108:109], v[160:161]
	v_pk_mul_f32 v[154:155], v[110:111], v[160:161]
	v_pk_mul_f32 v[156:157], v[100:101], v[160:161]
	v_pk_mul_f32 v[158:159], v[102:103], v[160:161]
	v_or_b32_e32 v170, 16, v140
	v_exp_f32_e32 v152, v152
	v_exp_f32_e32 v153, v153
	v_exp_f32_e32 v154, v154
	v_exp_f32_e32 v155, v155
	v_exp_f32_e32 v156, v156
	v_exp_f32_e32 v157, v157
	v_exp_f32_e32 v158, v158
	v_exp_f32_e32 v159, v159
	v_mad_i64_i32 v[166:167], s[18:19], v170, s73, v[134:135]
	v_pk_add_f32 v[152:153], v[152:153], v[162:163]
	v_pk_add_f32 v[154:155], v[154:155], v[162:163]
	v_pk_add_f32 v[156:157], v[156:157], v[162:163]
	v_pk_add_f32 v[158:159], v[158:159], v[162:163]
	v_rcp_f32_e32 v152, v152
	v_rcp_f32_e32 v153, v153
	v_rcp_f32_e32 v154, v154
	v_rcp_f32_e32 v155, v155
	v_rcp_f32_e32 v156, v156
	v_rcp_f32_e32 v157, v157
	v_rcp_f32_e32 v158, v158
	v_rcp_f32_e32 v159, v159
	v_lshl_add_u64 v[168:169], v[166:167], 0, v[164:165]
; __device__ __forceinline__ unsigned cvt_pk_bf16(float lo, float hi) { unsigned r; asm("v_cvt_pk_bf16_f32 %0, %1, %2" : "=v"(r) : "v"(lo), "v"(hi)); return r; }
; __device__ __forceinline__ float sigmoidf(float x) { return rcpf(1.0f + __expf(-x)); }
;     __device__ __forceinline__ void operator()(const f32x4 (&acc)[2][2][4][2], const pg8::Unit& u, int wr, int wc, int fr, int fq) const {
;         const int row0 = u.pm * 256 + wr * 64 + fr, col0 = u.pn * 128 + wc * 32 + 8 * fq;
; #pragma unroll
;         for (int ai = 0; ai < 2; ++ai)
; #pragma unroll
;             for (int m = 0; m < 4; ++m) { bf16_t* rowp = act + (size_t)(row0 + ai * 128 + m * 16) * FF + col0; float o[8];
; #pragma unroll
;                 for (int n = 0; n < 2; ++n) { const f32x4 gv = acc[ai][0][m][n], uv = acc[ai][1][m][n];
; #pragma unroll
;                     for (int j = 0; j < 4; ++j) o[4 * n + j] = gv[j] * sigmoidf(gv[j]) * uv[j]; }
;                 u32x4 w; w.x = cvt_pk_bf16(o[0], o[1]); w.y = cvt_pk_bf16(o[2], o[3]); w.z = cvt_pk_bf16(o[4], o[5]); w.w = cvt_pk_bf16(o[6], o[7]); *(u32x4*)rowp = w; }
	v_pk_mul_f32 v[108:109], v[108:109], v[152:153]
	v_pk_mul_f32 v[110:111], v[110:111], v[154:155]
	v_pk_mul_f32 v[100:101], v[100:101], v[156:157]
	v_pk_mul_f32 v[102:103], v[102:103], v[158:159]
	v_pk_mul_f32 v[108:109], v[108:109], v[104:105]
	v_pk_mul_f32 v[110:111], v[110:111], v[106:107]
	v_pk_mul_f32 v[100:101], v[100:101], v[96:97]
	v_pk_mul_f32 v[102:103], v[102:103], v[98:99]
	v_cvt_pk_bf16_f32 v104, v108, v109
	v_cvt_pk_bf16_f32 v105, v110, v111
	v_cvt_pk_bf16_f32 v106, v100, v101
	v_cvt_pk_bf16_f32 v107, v102, v103
	global_store_dwordx4 v[168:169], v[104:107], off
	v_pk_mul_f32 v[152:153], v[92:93], v[160:161]
	v_pk_mul_f32 v[154:155], v[94:95], v[160:161]
	v_pk_mul_f32 v[156:157], v[84:85], v[160:161]
	v_pk_mul_f32 v[158:159], v[86:87], v[160:161]
	v_or_b32_e32 v170, 32, v140
	v_exp_f32_e32 v152, v152
	v_exp_f32_e32 v153, v153
	v_exp_f32_e32 v154, v154
	v_exp_f32_e32 v155, v155
	v_exp_f32_e32 v156, v156
	v_exp_f32_e32 v157, v157
	v_exp_f32_e32 v158, v158
	v_exp_f32_e32 v159, v159
	v_mad_i64_i32 v[166:167], s[18:19], v170, s73, v[134:135]
	v_pk_add_f32 v[152:153], v[152:153], v[162:163]
	v_pk_add_f32 v[154:155], v[154:155], v[162:163]
	v_pk_add_f32 v[156:157], v[156:157], v[162:163]
	v_pk_add_f32 v[158:159], v[158:159], v[162:163]
	v_rcp_f32_e32 v152, v152
	v_rcp_f32_e32 v153, v153
	v_rcp_f32_e32 v154, v154
	v_rcp_f32_e32 v155, v155
	v_rcp_f32_e32 v156, v156
	v_rcp_f32_e32 v157, v157
	v_rcp_f32_e32 v158, v158
	v_rcp_f32_e32 v159, v159
	v_lshl_add_u64 v[168:169], v[166:167], 0, v[164:165]
	v_pk_mul_f32 v[92:93], v[92:93], v[152:153]
	v_pk_mul_f32 v[94:95], v[94:95], v[154:155]
	v_pk_mul_f32 v[84:85], v[84:85], v[156:157]
	v_pk_mul_f32 v[86:87], v[86:87], v[158:159]
	v_pk_mul_f32 v[92:93], v[92:93], v[88:89]
	v_pk_mul_f32 v[94:95], v[94:95], v[90:91]
	v_pk_mul_f32 v[84:85], v[84:85], v[80:81]
	v_pk_mul_f32 v[86:87], v[86:87], v[82:83]
	v_cvt_pk_bf16_f32 v88, v92, v93
	v_cvt_pk_bf16_f32 v89, v94, v95
	v_cvt_pk_bf16_f32 v90, v84, v85
	v_cvt_pk_bf16_f32 v91, v86, v87
	global_store_dwordx4 v[168:169], v[88:91], off
	v_pk_mul_f32 v[152:153], v[76:77], v[160:161]
	v_pk_mul_f32 v[154:155], v[78:79], v[160:161]
	v_pk_mul_f32 v[156:157], v[68:69], v[160:161]
	v_pk_mul_f32 v[158:159], v[70:71], v[160:161]
	v_or_b32_e32 v170, 48, v140
	v_exp_f32_e32 v152, v152
	v_exp_f32_e32 v153, v153
	v_exp_f32_e32 v154, v154
	v_exp_f32_e32 v155, v155
	v_exp_f32_e32 v156, v156
	v_exp_f32_e32 v157, v157
	v_exp_f32_e32 v158, v158
	v_exp_f32_e32 v159, v159
	v_mad_i64_i32 v[166:167], s[18:19], v170, s73, v[134:135]
	v_pk_add_f32 v[152:153], v[152:153], v[162:163]
	v_pk_add_f32 v[154:155], v[154:155], v[162:163]
	v_pk_add_f32 v[156:157], v[156:157], v[162:163]
	v_pk_add_f32 v[158:159], v[158:159], v[162:163]
	v_rcp_f32_e32 v152, v152
	v_rcp_f32_e32 v153, v153
	v_rcp_f32_e32 v154, v154
	v_rcp_f32_e32 v155, v155
	v_rcp_f32_e32 v156, v156
	v_rcp_f32_e32 v157, v157
	v_rcp_f32_e32 v158, v158
	v_rcp_f32_e32 v159, v159
	v_lshl_add_u64 v[168:169], v[166:167], 0, v[164:165]
	v_pk_mul_f32 v[76:77], v[76:77], v[152:153]
	v_pk_mul_f32 v[78:79], v[78:79], v[154:155]
	v_pk_mul_f32 v[68:69], v[68:69], v[156:157]
	v_pk_mul_f32 v[70:71], v[70:71], v[158:159]
	v_pk_mul_f32 v[76:77], v[76:77], v[72:73]
	v_pk_mul_f32 v[78:79], v[78:79], v[74:75]
	v_pk_mul_f32 v[68:69], v[68:69], v[64:65]
	v_pk_mul_f32 v[70:71], v[70:71], v[66:67]
	v_cvt_pk_bf16_f32 v72, v76, v77
	v_cvt_pk_bf16_f32 v73, v78, v79
	v_cvt_pk_bf16_f32 v74, v68, v69
	v_cvt_pk_bf16_f32 v75, v70, v71
	global_store_dwordx4 v[168:169], v[72:75], off
	v_pk_mul_f32 v[152:153], v[60:61], v[160:161]
	v_pk_mul_f32 v[154:155], v[62:63], v[160:161]
	v_pk_mul_f32 v[156:157], v[52:53], v[160:161]
	v_pk_mul_f32 v[158:159], v[54:55], v[160:161]
	v_add_u32_e32 v170, 0x80, v140
	v_exp_f32_e32 v152, v152
	v_exp_f32_e32 v153, v153
	v_exp_f32_e32 v154, v154
	v_exp_f32_e32 v155, v155
	v_exp_f32_e32 v156, v156
	v_exp_f32_e32 v157, v157
	v_exp_f32_e32 v158, v158
	v_exp_f32_e32 v159, v159
	v_mad_i64_i32 v[166:167], s[18:19], v170, s73, v[134:135]
	v_pk_add_f32 v[152:153], v[152:153], v[162:163]
	v_pk_add_f32 v[154:155], v[154:155], v[162:163]
	v_pk_add_f32 v[156:157], v[156:157], v[162:163]
	v_pk_add_f32 v[158:159], v[158:159], v[162:163]
	v_rcp_f32_e32 v152, v152
	v_rcp_f32_e32 v153, v153
	v_rcp_f32_e32 v154, v154
	v_rcp_f32_e32 v155, v155
	v_rcp_f32_e32 v156, v156
	v_rcp_f32_e32 v157, v157
	v_rcp_f32_e32 v158, v158
	v_rcp_f32_e32 v159, v159
	v_lshl_add_u64 v[168:169], v[166:167], 0, v[164:165]
	v_pk_mul_f32 v[60:61], v[60:61], v[152:153]
	v_pk_mul_f32 v[62:63], v[62:63], v[154:155]
	v_pk_mul_f32 v[52:53], v[52:53], v[156:157]
	v_pk_mul_f32 v[54:55], v[54:55], v[158:159]
	v_pk_mul_f32 v[60:61], v[60:61], v[56:57]
	v_pk_mul_f32 v[62:63], v[62:63], v[58:59]
	v_pk_mul_f32 v[52:53], v[52:53], v[48:49]
; __device__ __forceinline__ unsigned cvt_pk_bf16(float lo, float hi) { unsigned r; asm("v_cvt_pk_bf16_f32 %0, %1, %2" : "=v"(r) : "v"(lo), "v"(hi)); return r; }
; __device__ __forceinline__ float sigmoidf(float x) { return rcpf(1.0f + __expf(-x)); }
; #define PG8_WAIT_V(n) asm volatile("s_waitcnt vmcnt(" #n ")" ::: "memory")
; #define PG8_BAR __builtin_amdgcn_s_barrier()
; template <class Epi, class Sched>
; __device__ __forceinline__ void gemm_phase(LAS unsigned char* lds, const Gemm g, const Sched& S, const Epi& E, const Ids I) {
;     ...
;         E(acc, cur, wr, wc, fr, fq);
;         if (!has_next) break;
; #pragma unroll
;         for (int a = 0; a < 2; ++a)
; #pragma unroll
;             for (int b = 0; b < 2; ++b)
; #pragma unroll
;                 for (int m = 0; m < 4; ++m)
; #pragma unroll
;                     for (int n = 0; n < 2; ++n) acc[a][b][m][n] = (f32x4){0.f, 0.f, 0.f, 0.f};
;         cur = nxt; cA = nA; cB = nB; ++ui;
;     }
;     PG8_WAIT_V(0);
;     if (wr == 0) PG8_BAR;
;     PG8_BAR;
;     __device__ __forceinline__ void operator()(const f32x4 (&acc)[2][2][4][2], const pg8::Unit& u, int wr, int wc, int fr, int fq) const {
;         const int row0 = u.pm * 256 + wr * 64 + fr, col0 = u.pn * 128 + wc * 32 + 8 * fq;
; #pragma unroll
;         for (int ai = 0; ai < 2; ++ai)
; #pragma unroll
;             for (int m = 0; m < 4; ++m) { bf16_t* rowp = act + (size_t)(row0 + ai * 128 + m * 16) * FF + col0; float o[8];
; #pragma unroll
;                 for (int n = 0; n < 2; ++n) { const f32x4 gv = acc[ai][0][m][n], uv = acc[ai][1][m][n];
; #pragma unroll
;                     for (int j = 0; j < 4; ++j) o[4 * n + j] = gv[j] * sigmoidf(gv[j]) * uv[j]; }
;                 u32x4 w; w.x = cvt_pk_bf16(o[0], o[1]); w.y = cvt_pk_bf16(o[2], o[3]); w.z = cvt_pk_bf16(o[4], o[5]); w.w = cvt_pk_bf16(o[6], o[7]); *(u32x4*)rowp = w; }
	v_pk_mul_f32 v[54:55], v[54:55], v[50:51]
	v_cvt_pk_bf16_f32 v56, v60, v61
	v_cvt_pk_bf16_f32 v57, v62, v63
	v_cvt_pk_bf16_f32 v58, v52, v53
	v_cvt_pk_bf16_f32 v59, v54, v55
	global_store_dwordx4 v[168:169], v[56:59], off
	v_pk_mul_f32 v[152:153], v[44:45], v[160:161]
	v_pk_mul_f32 v[154:155], v[46:47], v[160:161]
	v_pk_mul_f32 v[156:157], v[36:37], v[160:161]
	v_pk_mul_f32 v[158:159], v[38:39], v[160:161]
	v_add_u32_e32 v170, 0x90, v140
	v_exp_f32_e32 v152, v152
	v_exp_f32_e32 v153, v153
	v_exp_f32_e32 v154, v154
	v_exp_f32_e32 v155, v155
	v_exp_f32_e32 v156, v156
	v_exp_f32_e32 v157, v157
	v_exp_f32_e32 v158, v158
	v_exp_f32_e32 v159, v159
	v_mad_i64_i32 v[166:167], s[18:19], v170, s73, v[134:135]
	v_pk_add_f32 v[152:153], v[152:153], v[162:163]
	v_pk_add_f32 v[154:155], v[154:155], v[162:163]
	v_pk_add_f32 v[156:157], v[156:157], v[162:163]
	v_pk_add_f32 v[158:159], v[158:159], v[162:163]
	v_rcp_f32_e32 v152, v152
	v_rcp_f32_e32 v153, v153
	v_rcp_f32_e32 v154, v154
	v_rcp_f32_e32 v155, v155
	v_rcp_f32_e32 v156, v156
	v_rcp_f32_e32 v157, v157
	v_rcp_f32_e32 v158, v158
	v_rcp_f32_e32 v159, v159
	v_lshl_add_u64 v[168:169], v[166:167], 0, v[164:165]
	v_pk_mul_f32 v[44:45], v[44:45], v[152:153]
	v_pk_mul_f32 v[46:47], v[46:47], v[154:155]
	v_pk_mul_f32 v[36:37], v[36:37], v[156:157]
	v_pk_mul_f32 v[38:39], v[38:39], v[158:159]
	v_pk_mul_f32 v[44:45], v[44:45], v[40:41]
	v_pk_mul_f32 v[46:47], v[46:47], v[42:43]
	v_pk_mul_f32 v[36:37], v[36:37], v[32:33]
	v_pk_mul_f32 v[38:39], v[38:39], v[34:35]
	v_cvt_pk_bf16_f32 v40, v44, v45
	v_cvt_pk_bf16_f32 v41, v46, v47
	v_cvt_pk_bf16_f32 v42, v36, v37
	v_cvt_pk_bf16_f32 v43, v38, v39
	global_store_dwordx4 v[168:169], v[40:43], off
	v_pk_mul_f32 v[152:153], v[28:29], v[160:161]
	v_pk_mul_f32 v[154:155], v[30:31], v[160:161]
	v_pk_mul_f32 v[156:157], v[20:21], v[160:161]
	v_pk_mul_f32 v[158:159], v[22:23], v[160:161]
	v_add_u32_e32 v170, 0xa0, v140
	v_exp_f32_e32 v152, v152
	v_exp_f32_e32 v153, v153
	v_exp_f32_e32 v154, v154
	v_exp_f32_e32 v155, v155
	v_exp_f32_e32 v156, v156
	v_exp_f32_e32 v157, v157
	v_exp_f32_e32 v158, v158
	v_exp_f32_e32 v159, v159
	v_mad_i64_i32 v[166:167], s[18:19], v170, s73, v[134:135]
	v_pk_add_f32 v[152:153], v[152:153], v[162:163]
	v_pk_add_f32 v[154:155], v[154:155], v[162:163]
	v_pk_add_f32 v[156:157], v[156:157], v[162:163]
	v_pk_add_f32 v[158:159], v[158:159], v[162:163]
	v_rcp_f32_e32 v152, v152
	v_rcp_f32_e32 v153, v153
	v_rcp_f32_e32 v154, v154
	v_rcp_f32_e32 v155, v155
	v_rcp_f32_e32 v156, v156
	v_rcp_f32_e32 v157, v157
	v_rcp_f32_e32 v158, v158
	v_rcp_f32_e32 v159, v159
	v_lshl_add_u64 v[168:169], v[166:167], 0, v[164:165]
	v_pk_mul_f32 v[28:29], v[28:29], v[152:153]
	v_pk_mul_f32 v[30:31], v[30:31], v[154:155]
	v_pk_mul_f32 v[20:21], v[20:21], v[156:157]
	v_pk_mul_f32 v[22:23], v[22:23], v[158:159]
	v_pk_mul_f32 v[28:29], v[28:29], v[24:25]
	v_pk_mul_f32 v[30:31], v[30:31], v[26:27]
	v_pk_mul_f32 v[20:21], v[20:21], v[16:17]
	v_pk_mul_f32 v[22:23], v[22:23], v[18:19]
	v_cvt_pk_bf16_f32 v24, v28, v29
	v_cvt_pk_bf16_f32 v25, v30, v31
	v_cvt_pk_bf16_f32 v26, v20, v21
	v_cvt_pk_bf16_f32 v27, v22, v23
	global_store_dwordx4 v[168:169], v[24:27], off
	v_pk_mul_f32 v[152:153], v[12:13], v[160:161]
	v_pk_mul_f32 v[154:155], v[14:15], v[160:161]
	v_pk_mul_f32 v[156:157], v[4:5], v[160:161]
	v_pk_mul_f32 v[158:159], v[6:7], v[160:161]
	v_add_u32_e32 v170, 0xb0, v140
	v_exp_f32_e32 v152, v152
	v_exp_f32_e32 v153, v153
	v_exp_f32_e32 v154, v154
	v_exp_f32_e32 v155, v155
	v_exp_f32_e32 v156, v156
	v_exp_f32_e32 v157, v157
	v_exp_f32_e32 v158, v158
	v_exp_f32_e32 v159, v159
	v_mad_i64_i32 v[166:167], s[18:19], v170, s73, v[134:135]
	v_pk_add_f32 v[152:153], v[152:153], v[162:163]
	v_pk_add_f32 v[154:155], v[154:155], v[162:163]
	v_pk_add_f32 v[156:157], v[156:157], v[162:163]
	v_pk_add_f32 v[158:159], v[158:159], v[162:163]
	v_rcp_f32_e32 v152, v152
	v_rcp_f32_e32 v153, v153
	v_rcp_f32_e32 v154, v154
	v_rcp_f32_e32 v155, v155
	v_rcp_f32_e32 v156, v156
	v_rcp_f32_e32 v157, v157
	v_rcp_f32_e32 v158, v158
	v_rcp_f32_e32 v159, v159
	v_lshl_add_u64 v[168:169], v[166:167], 0, v[164:165]
	v_pk_mul_f32 v[12:13], v[12:13], v[152:153]
	v_pk_mul_f32 v[14:15], v[14:15], v[154:155]
	v_pk_mul_f32 v[4:5], v[4:5], v[156:157]
	v_pk_mul_f32 v[6:7], v[6:7], v[158:159]
	v_pk_mul_f32 v[12:13], v[12:13], v[8:9]
	v_pk_mul_f32 v[14:15], v[14:15], v[10:11]
	v_pk_mul_f32 v[4:5], v[4:5], v[0:1]
	v_pk_mul_f32 v[6:7], v[6:7], v[2:3]
	v_cvt_pk_bf16_f32 v8, v12, v13
	v_cvt_pk_bf16_f32 v9, v14, v15
	v_cvt_pk_bf16_f32 v10, v4, v5
	v_cvt_pk_bf16_f32 v11, v6, v7
	global_store_dwordx4 v[168:169], v[8:11], off
	s_nop 1
	s_mov_b64 s[18:19], s[10:11]
	s_and_b64 vcc, exec, s[4:5]
	s_cbranch_vccz .LBB0_401
	s_waitcnt vmcnt(0)
	s_cmpk_gt_u32 s24, 0xff
	v_readlane_b32 s34, v254, 46
	s_cbranch_scc1 .LBB0_412
	s_barrier

; __device__ __forceinline__ void phase_m2(PP P, int l, LAS unsigned char* lds, const Ids I) {
;     ...
;     for (int idx = tid; idx < 5 * 136; idx += 512) { SGH[11 * 136 + idx] = (bf16_t)0; SGL[11 * 136 + idx] = (bf16_t)0; }
;     for (int u = BID; u < MT / 11; u += NB) {
;         const int r0 = u * 11;
; #pragma unroll
;         for (int i = 0; i < 3; ++i) { const int idx = tid + 512 * i; if (idx < 11 * 128) { const int tok = idx >> 7, col = idx & 127, r = r0 + tok, t = t_in_seq(r);
;             const float cur = bf2f(PR[(size_t)r * INW + 2688 + col]);
;             const float prev = t > 0 ? bf2f(PR[(size_t)(r - 1) * INW + 2688 + col]) : (r < MTP ? 0.f : P->in[I_SSHIFT][((size_t)l * 128 + ((r - MTP) >> 2)) * PW + 1664 + col]);
;             const float sg = sigmoidf(cur + (prev - cur) * mu[1664 + col]); const bf16_t h = f2bf(sg);
;             SGH[tok * 136 + col] = h; SGL[tok * 136 + col] = f2bf(sg - bf2f(h)); } }
; #pragma unroll
;         for (int i = 0; i < 2; ++i) { const int idx = tid + 512 * i; if (idx < 11 * 64) { const int tok = idx >> 6, c8 = (idx & 63) * 8; const size_t r = (size_t)r0 + tok; float f[8];
;             unpack8(*(const u32x4*)(ymix + r * 1024 + 512 + c8), f); *(LAS f32x4*)(LY + tok * 512 + c8) = (f32x4){f[0], f[1], f[2], f[3]}; *(LAS f32x4*)(LY + tok * 512 + c8 + 4) = (f32x4){f[4], f[5], f[6], f[7]};
;             unpack8(*(const u32x4*)(arr + A_R * AS + r * 512 + c8), f); *(LAS f32x4*)(LR + tok * 512 + c8) = (f32x4){f[0], f[1], f[2], f[3]}; *(LAS f32x4*)(LR + tok * 512 + c8 + 4) = (f32x4){f[4], f[5], f[6], f[7]};
;             unpack8(*(const u32x4*)(arr + A_KF * AS + r * 512 + c8), f); *(LAS f32x4*)(LK + tok * 512 + c8) = (f32x4){f[0], f[1], f[2], f[3]}; *(LAS f32x4*)(LK + tok * 512 + c8 + 4) = (f32x4){f[4], f[5], f[6], f[7]};
;             unpack8(*(const u32x4*)(arr + A_V * AS + r * 512 + c8), f); *(LAS f32x4*)(LV + tok * 512 + c8) = (f32x4){f[0], f[1], f[2], f[3]}; *(LAS f32x4*)(LV + tok * 512 + c8 + 4) = (f32x4){f[4], f[5], f[6], f[7]}; } }
;         __syncthreads();
;         { f32x4 ag[4];
; #pragma unroll
;           for (int nt = 0; nt < 4; ++nt) ag[nt] = (f32x4){0.f, 0.f, 0.f, 0.f};
; #pragma unroll
;           for (int ks = 0; ks < 4; ++ks) { const bf16x8 fh = *(const LAS bf16x8*)(SGH + l15 * 136 + ks * 32 + quad * 8), fl = *(const LAS bf16x8*)(SGL + l15 * 136 + ks * 32 + quad * 8);
; #pragma unroll
.LBB0_430:
	s_or_b64 exec, exec, s[6:7]
	s_cmpk_gt_i32 s93, 0x5ff
	s_cbranch_scc1 .LBB0_499
	v_readlane_b32 s1, v254, 42
	s_add_u32 s4, s4, s1
	v_and_b32_e32 v154, 0x7f, v128
	s_addc_u32 s5, s5, 0
	s_lshl_b32 s0, s0, 2
	v_lshlrev_b32_e32 v144, 2, v154
	s_add_i32 s3, s0, 0
	v_lshl_add_u64 v[130:131], s[4:5], 0, v[144:145]
	s_mov_b64 s[0:1], 0x1a00
	v_lshlrev_b32_e32 v129, 3, v136
	v_lshl_add_u64 v[156:157], v[130:131], 0, s[0:1]
	v_and_b32_e32 v129, 0x1f8, v129
	v_readlane_b32 s0, v254, 35
	v_lshlrev_b32_e32 v144, 1, v129
	v_readlane_b32 s1, v254, 36
	v_lshlrev_b32_e32 v130, 2, v129
	v_add_u32_e32 v132, 0, v130
	v_lshl_add_u64 v[158:159], s[0:1], 0, v[144:145]
	v_readlane_b32 s0, v254, 37
	v_readlane_b32 s1, v254, 38
	s_add_i32 s3, s3, 0x18200
	v_lshlrev_b32_e32 v131, 1, v139
	v_lshl_add_u64 v[160:161], s[0:1], 0, v[144:145]
	v_readlane_b32 s0, v254, 39
	v_readlane_b32 s1, v254, 40
	v_lshl_add_u32 v134, v138, 2, s3
	v_ashrrev_i32_e32 v188, 7, v128
	v_lshl_add_u64 v[162:163], s[0:1], 0, v[144:145]
	v_readlane_b32 s0, v254, 6
	s_movk_i32 s3, 0x88
	v_add_u32_e32 v135, 0x200, v128
	v_add_u32_e32 v129, s0, v130
	v_mul_u32_u24_e32 v130, 0x88, v138
	v_lshlrev_b32_e32 v130, 1, v130
	s_movk_i32 s0, 0x580
	v_add3_u32 v187, 0, v130, v131
	v_cmp_gt_i32_e64 s[4:5], s0, v128
	v_mad_u64_u32 v[130:131], s[0:1], v188, s3, v[154:155]
	s_movk_i32 s0, 0x380
	v_ashrrev_i32_e32 v190, 7, v135
	v_lshl_add_u32 v189, v130, 1, 0
	v_cmp_gt_i32_e64 s[6:7], s0, v128
	v_mad_u64_u32 v[130:131], s[0:1], v190, s3, v[154:155]
	v_lshl_add_u32 v191, v130, 1, 0
	v_add_u32_e32 v130, 0x400, v128
	s_movk_i32 s0, 0x180
	v_ashrrev_i32_e32 v192, 7, v130
	v_cmp_gt_i32_e64 s[8:9], s0, v128
	v_mad_u64_u32 v[130:131], s[0:1], v192, s3, v[154:155]
	s_movk_i32 s0, 0x2c0
	s_nop 0
	v_cmp_gt_i32_e64 s[10:11], s0, v128
	v_ashrrev_i32_e32 v164, 6, v128
	s_movk_i32 s0, 0xc0
	v_ashrrev_i32_e32 v166, 6, v135
	v_lshlrev_b32_e32 v133, 2, v137
	v_lshl_add_u32 v193, v130, 1, 0
	v_lshlrev_b32_e32 v130, 11, v164
	v_cmp_gt_i32_e64 s[12:13], s0, v128
	v_lshlrev_b32_e32 v128, 11, v166
	v_add_u32_e32 v194, v132, v130
	v_add_u32_e32 v195, v129, v130
	v_add_u32_e32 v197, v129, v128
	v_or_b32_e32 v129, 1, v133
	v_or_b32_e32 v130, 2, v133
	v_or_b32_e32 v131, 3, v133
	s_lshl_b32 s0, s25, 8
	v_add_u32_e32 v196, v132, v128
	v_lshlrev_b32_e32 v128, 13, v137
	v_cmp_gt_u32_e64 s[16:17], 11, v129
	v_lshlrev_b32_e32 v129, 11, v129
	v_cmp_gt_u32_e64 s[18:19], 11, v130
	v_lshlrev_b32_e32 v130, 11, v130
	v_cmp_gt_u32_e64 s[20:21], 11, v131
	v_lshlrev_b32_e32 v131, 11, v131
	s_add_i32 s0, s0, 0
	v_ashrrev_i32_e32 v165, 31, v164
	v_ashrrev_i32_e32 v167, 31, v166
	v_cmp_ne_u32_e64 s[14:15], 3, v137
	v_lshl_add_u64 v[168:169], s[78:79], 0, v[144:145]
	v_lshl_add_u32 v198, v136, 2, s0
	v_add_u32_e32 v199, v134, v128
	v_add_u32_e32 v200, v134, v129
	v_add_u32_e32 v201, v134, v130
	v_add_u32_e32 v202, v134, v131
	s_mov_b32 s3, s93
	s_branch .LBB0_433
	s_nop 0
	s_nop 0
	s_nop 0
	s_nop 0
	s_nop 0
	s_nop 0
	s_nop 0
	s_nop 0
	s_nop 0
	s_nop 0
	s_nop 0
	s_nop 0
	s_nop 0
	s_nop 0
	s_nop 0
	s_nop 0
	s_nop 0
	s_nop 0
	s_nop 0
	s_nop 0
	s_nop 0
	s_nop 0
	s_nop 0
	s_nop 0
	s_nop 0
	s_nop 0
	s_nop 0
	s_nop 0
	s_nop 0
	s_nop 0
	s_nop 0
	s_nop 0
	s_nop 0
	s_nop 0
	s_nop 0
	s_nop 0
	s_nop 0
	s_nop 0
	s_nop 0
	s_nop 0
	s_nop 0
	s_nop 0
	s_nop 0
	s_nop 0
	s_nop 0
